# chain loop counted vmcnt waits exact for steady iterations, per wave kind (loader / non-loader); conservative counts kept for first and last iteration
# speedup vs baseline: 1.0069x; 1.0034x over previous
.LBB0_1217:
	s_or_b64 exec, exec, s[22:23]
	s_and_saveexec_b64 s[22:23], s[8:9]
	s_cbranch_execz .LBB0_1219
	s_cmp_lg_u32 s29, -8
	s_cbranch_scc1 .Lc4_s_0
	s_waitcnt vmcnt(19)
.Lc4_s_0:
	s_waitcnt vmcnt(25)
	ds_write_b128 v131, v[22:25] offset:4608
.LBB0_1219:
	s_or_b64 exec, exec, s[22:23]
	v_mov_b32_e32 v110, s28
	ds_read_b128 v[134:137], v133
	ds_read_b64 v[110:111], v110
	ds_read_b128 v[138:141], v133 offset:64
	ds_read_b128 v[146:149], v133 offset:2304
	s_cmp_lg_u32 s29, -8
	s_cbranch_scc1 .Lc4_s_1
	s_waitcnt vmcnt(16)
.Lc4_s_1:
	s_cmp_lg_u64 s[8:9], 0
	s_cbranch_scc1 .Lc4_l_1
	s_waitcnt vmcnt(23) lgkmcnt(3)
	s_branch .Lc4_e_1
.Lc4_l_1:
	s_waitcnt vmcnt(31) lgkmcnt(3)
.Lc4_e_1:
	v_mfma_f32_16x16x32_bf16 v[142:145], v[2:5], v[134:137], 0
	s_waitcnt lgkmcnt(2)
	v_add_f32_e32 v110, v115, v110
	v_max_f32_e32 v111, v111, v111
	v_max_f32_e32 v134, v110, v111
	v_sub_f32_e32 v110, v110, v134
	v_mul_f32_e32 v110, 0x3fb8aa3b, v110
	v_exp_f32_e32 v110, v110
	v_mul_f32_e32 v111, 0xbfb8aa3b, v134
	s_cmp_lg_u32 s29, -8
	s_cbranch_scc1 .Lc4_s_2
	s_waitcnt vmcnt(15)
.Lc4_s_2:
	s_cmp_lg_u64 s[8:9], 0
	s_cbranch_scc1 .Lc4_l_2
	s_waitcnt vmcnt(22) lgkmcnt(1)
	s_branch .Lc4_e_2
.Lc4_l_2:
	s_waitcnt vmcnt(30) lgkmcnt(1)
.Lc4_e_2:
	v_mfma_f32_16x16x32_bf16 v[136:139], v[6:9], v[138:141], v[142:145]
	v_mul_f32_e64 v114, v126, v110
	v_mul_f32_e64 v115, v127, v110
	v_pk_mul_f32 v[124:125], v[124:125], v[110:111] op_sel_hi:[1,0]
	ds_read_b128 v[140:143], v133 offset:2368
	s_waitcnt lgkmcnt(1)
	v_mfma_f32_16x16x32_bf16 v[144:147], v[2:5], v[146:149], 0
	v_exp_f32_e32 v148, v111
	s_nop 0
	v_pk_fma_f32 v[124:125], v[138:139], v[148:149], v[124:125] op_sel_hi:[1,0,1]
	v_pk_fma_f32 v[128:129], v[136:137], v[148:149], v[114:115] op_sel_hi:[1,0,1]
	v_mfma_f32_16x16x32_bf16 v[136:139], v[2:5], v[86:89], 0
	s_waitcnt lgkmcnt(0)
	v_mfma_f32_16x16x32_bf16 v[140:143], v[6:9], v[140:143], v[144:147]
	v_mfma_f32_16x16x32_bf16 v[136:139], v[6:9], v[86:89], v[136:139]
	s_nop 6
	v_mul_f32_e64 v114, v148, v142
	v_mul_f32_e64 v115, v148, v143
	v_pk_mul_f32 v[126:127], v[148:149], v[140:141] op_sel_hi:[0,1]
	v_pk_fma_f32 v[114:115], v[122:123], v[110:111], v[114:115] op_sel_hi:[1,0,1]
	v_pk_fma_f32 v[118:119], v[118:119], v[110:111], v[126:127] op_sel_hi:[1,0,1]
	v_pk_mul_f32 v[122:123], v[110:111], v[120:121] op_sel_hi:[0,1]
	v_pk_mul_f32 v[110:111], v[110:111], v[116:117] op_sel_hi:[0,1]
	v_pk_fma_f32 v[120:121], v[148:149], v[138:139], v[110:111] op_sel_hi:[0,1,1]
	v_lshl_add_u64 v[110:111], s[16:17], 0, v[104:105]
	v_pk_fma_f32 v[126:127], v[148:149], v[136:137], v[122:123] op_sel_hi:[0,1,1]
	v_cvt_pk_bf16_f32 v136, v128, v129
	v_cvt_pk_bf16_f32 v138, v118, v119
	v_cvt_pk_bf16_f32 v137, v124, v125
	v_cvt_pk_bf16_f32 v139, v114, v115
	v_add_co_u32_e32 v116, vcc, 0x9008000, v110
	v_permlane16_swap_b32_e32 v136, v138
	v_permlane16_swap_b32_e32 v137, v139
	v_addc_co_u32_e32 v117, vcc, 0, v111, vcc
	ds_write_b128 v247, v[136:139] offset:0
	s_waitcnt lgkmcnt(0)
	s_barrier
	s_add_i32 s22, s29, 9
	s_cmp_gt_u32 s22, 56
	s_cbranch_scc1 .LBB0_1227
	v_add_co_u32_e32 v6, vcc, 0xd020000, v112
	s_nop 1
	v_addc_co_u32_e32 v7, vcc, 0, v113, vcc
	global_load_dwordx4 v[2:5], v[6:7], off
	s_nop 0
	global_load_dwordx4 v[6:9], v[6:7], off offset:64
	s_and_saveexec_b64 s[22:23], s[8:9]
	s_cbranch_execz .LBB0_1226
	v_lshl_add_u64 v[10:11], s[16:17], 0, v[106:107]
	v_add_co_u32_e32 v10, vcc, 0xe020000, v10
	s_nop 1
	v_addc_co_u32_e32 v11, vcc, 0, v11, vcc
	global_load_dwordx4 v[10:13], v[10:11], off

.LBB0_1227:
	s_and_saveexec_b64 s[22:23], s[8:9]
	s_cbranch_execz .LBB0_1229
	s_cmp_lg_u32 s29, -8
	s_cbranch_scc1 .Lc4_s_3
	s_waitcnt vmcnt(19)
.Lc4_s_3:
	s_waitcnt vmcnt(24)
	ds_write_b128 v131, v[34:37] offset:9216

.LBB0_1223:
	s_or_b64 exec, exec, s[98:99]
	v_mov_b32_e32 v116, s28
	ds_read_b128 v[136:139], v133 offset:4608
	ds_read_b64 v[116:117], v116 offset:8
	ds_read_b128 v[140:143], v133 offset:4672
	ds_read_b128 v[144:147], v133 offset:6912
	s_cmp_lg_u32 s29, -8
	s_cbranch_scc1 .Lc4_s_4
	s_waitcnt vmcnt(17)

.Lc4_e_4:
	v_mfma_f32_16x16x32_bf16 v[136:139], v[14:17], v[136:139], 0
	s_waitcnt lgkmcnt(2)
	v_add_f32_e32 v116, v134, v116
	v_max_f32_e32 v117, v117, v117
	v_max_f32_e32 v134, v116, v117
	v_sub_f32_e32 v116, v116, v134
	v_mul_f32_e32 v116, 0x3fb8aa3b, v116
	v_exp_f32_e32 v148, v116
	v_mul_f32_e32 v116, 0xbfb8aa3b, v134
	s_cmp_lg_u32 s29, -8
	s_cbranch_scc1 .Lc4_s_5
	s_waitcnt vmcnt(16)

.Lc4_e_5:
	v_mfma_f32_16x16x32_bf16 v[136:139], v[18:21], v[140:143], v[136:139]
	v_exp_f32_e32 v150, v116
	ds_read_b128 v[140:143], v133 offset:6976
	v_pk_mul_f32 v[116:117], v[128:129], v[148:149] op_sel_hi:[1,0]
	s_waitcnt lgkmcnt(1)
	v_mfma_f32_16x16x32_bf16 v[144:147], v[14:17], v[144:147], 0
	v_mul_f32_e64 v122, v124, v148
	v_mul_f32_e64 v123, v125, v148
	s_nop 0
	v_pk_fma_f32 v[128:129], v[136:137], v[150:151], v[116:117] op_sel_hi:[1,0,1]
	v_pk_fma_f32 v[124:125], v[138:139], v[150:151], v[122:123] op_sel_hi:[1,0,1]
	v_mfma_f32_16x16x32_bf16 v[136:139], v[14:17], v[86:89], 0
	s_waitcnt lgkmcnt(0)
	v_mfma_f32_16x16x32_bf16 v[140:143], v[18:21], v[140:143], v[144:147]
	v_mfma_f32_16x16x32_bf16 v[136:139], v[18:21], v[86:89], v[136:139]
	s_nop 6
	v_mul_f32_e64 v116, v150, v142
	v_mul_f32_e64 v117, v150, v143
	v_pk_mul_f32 v[122:123], v[150:151], v[140:141] op_sel_hi:[0,1]
	v_pk_fma_f32 v[116:117], v[114:115], v[148:149], v[116:117] op_sel_hi:[1,0,1]
	v_pk_fma_f32 v[122:123], v[118:119], v[148:149], v[122:123] op_sel_hi:[1,0,1]
	v_pk_mul_f32 v[114:115], v[150:151], v[138:139] op_sel_hi:[0,1]
	v_pk_mul_f32 v[118:119], v[150:151], v[136:137] op_sel_hi:[0,1]
	v_pk_fma_f32 v[114:115], v[120:121], v[148:149], v[114:115] op_sel_hi:[1,0,1]
	v_cvt_pk_bf16_f32 v136, v128, v129
	v_cvt_pk_bf16_f32 v138, v122, v123
	v_cvt_pk_bf16_f32 v137, v124, v125
	v_cvt_pk_bf16_f32 v139, v116, v117
	v_add_co_u32_e32 v120, vcc, 0x9010000, v110
	v_pk_fma_f32 v[118:119], v[126:127], v[148:149], v[118:119] op_sel_hi:[1,0,1]
	v_permlane16_swap_b32_e32 v136, v138
	v_permlane16_swap_b32_e32 v137, v139
	v_addc_co_u32_e32 v121, vcc, 0, v111, vcc
	ds_write_b128 v247, v[136:139] offset:8704
	s_waitcnt lgkmcnt(0)
	s_barrier
	s_add_i32 s22, s29, 10
	s_cmp_gt_u32 s22, 56
	s_cbranch_scc1 .LBB0_1237
	v_add_co_u32_e32 v18, vcc, 0xd024000, v112
	s_nop 1
	v_addc_co_u32_e32 v19, vcc, 0, v113, vcc
	global_load_dwordx4 v[14:17], v[18:19], off
	s_nop 0
	global_load_dwordx4 v[18:21], v[18:19], off offset:64
	s_and_saveexec_b64 s[22:23], s[8:9]
	s_cbranch_execz .LBB0_1236
	v_lshl_add_u64 v[22:23], s[16:17], 0, v[106:107]
	v_add_co_u32_e32 v22, vcc, 0xe024000, v22
	s_nop 1
	v_addc_co_u32_e32 v23, vcc, 0, v23, vcc
	global_load_dwordx4 v[22:25], v[22:23], off

.LBB0_1237:
	s_and_saveexec_b64 s[22:23], s[8:9]
	s_cbranch_execz .LBB0_1239
	s_cmp_lg_u32 s29, -8
	s_cbranch_scc1 .Lc4_s_6
	s_waitcnt vmcnt(20)
.Lc4_s_6:
	s_waitcnt vmcnt(24)
	ds_write_b128 v131, v[46:49] offset:13824

.LBB0_1233:
	s_or_b64 exec, exec, s[98:99]
	v_mov_b32_e32 v120, s28
	ds_read_b128 v[136:139], v133 offset:9216
	ds_read_b64 v[120:121], v120 offset:16
	ds_read_b128 v[140:143], v133 offset:9280
	ds_read_b128 v[144:147], v133 offset:11520
	s_cmp_lg_u32 s29, -8
	s_cbranch_scc1 .Lc4_s_7
	s_waitcnt vmcnt(18)

.Lc4_e_7:
	v_mfma_f32_16x16x32_bf16 v[136:139], v[26:29], v[136:139], 0
	s_waitcnt lgkmcnt(2)
	v_add_f32_e32 v120, v134, v120
	v_max_f32_e32 v121, v121, v121
	v_max_f32_e32 v134, v120, v121
	v_sub_f32_e32 v120, v120, v134
	v_mul_f32_e32 v120, 0x3fb8aa3b, v120
	v_exp_f32_e32 v148, v120
	v_mul_f32_e32 v120, 0xbfb8aa3b, v134
	s_cmp_lg_u32 s29, -8
	s_cbranch_scc1 .Lc4_s_8
	s_waitcnt vmcnt(17)

.Lc4_e_8:
	v_mfma_f32_16x16x32_bf16 v[136:139], v[30:33], v[140:143], v[136:139]
	v_exp_f32_e32 v150, v120
	ds_read_b128 v[140:143], v133 offset:11584
	v_pk_mul_f32 v[120:121], v[128:129], v[148:149] op_sel_hi:[1,0]
	s_waitcnt lgkmcnt(1)
	v_mfma_f32_16x16x32_bf16 v[144:147], v[26:29], v[144:147], 0
	v_mul_f32_e64 v124, v124, v148
	v_mul_f32_e64 v125, v125, v148
	s_nop 0
	v_pk_fma_f32 v[126:127], v[136:137], v[150:151], v[120:121] op_sel_hi:[1,0,1]
	v_pk_fma_f32 v[124:125], v[138:139], v[150:151], v[124:125] op_sel_hi:[1,0,1]
	v_mfma_f32_16x16x32_bf16 v[136:139], v[26:29], v[86:89], 0
	s_waitcnt lgkmcnt(0)
	v_mfma_f32_16x16x32_bf16 v[140:143], v[30:33], v[140:143], v[144:147]
	v_mfma_f32_16x16x32_bf16 v[136:139], v[30:33], v[86:89], v[136:139]
	s_nop 6
	v_mul_f32_e64 v120, v150, v142
	v_mul_f32_e64 v121, v150, v143
	v_pk_mul_f32 v[128:129], v[150:151], v[140:141] op_sel_hi:[0,1]
	v_pk_fma_f32 v[116:117], v[116:117], v[148:149], v[120:121] op_sel_hi:[1,0,1]
	v_pk_fma_f32 v[120:121], v[122:123], v[148:149], v[128:129] op_sel_hi:[1,0,1]
	v_pk_mul_f32 v[122:123], v[150:151], v[138:139] op_sel_hi:[0,1]
	v_pk_mul_f32 v[128:129], v[150:151], v[136:137] op_sel_hi:[0,1]
	v_pk_fma_f32 v[114:115], v[114:115], v[148:149], v[122:123] op_sel_hi:[1,0,1]
	v_cvt_pk_bf16_f32 v136, v126, v127
	v_cvt_pk_bf16_f32 v138, v120, v121
	v_cvt_pk_bf16_f32 v137, v124, v125
	v_cvt_pk_bf16_f32 v139, v116, v117
	v_add_co_u32_e32 v122, vcc, 0x9018000, v110
	v_pk_fma_f32 v[118:119], v[118:119], v[148:149], v[128:129] op_sel_hi:[1,0,1]
	v_permlane16_swap_b32_e32 v136, v138
	v_permlane16_swap_b32_e32 v137, v139
	v_addc_co_u32_e32 v123, vcc, 0, v111, vcc
	ds_write_b128 v247, v[136:139] offset:0
	s_waitcnt lgkmcnt(0)
	s_barrier
	s_add_i32 s22, s29, 11
	s_cmp_gt_u32 s22, 56
	s_cbranch_scc1 .LBB0_1247
	v_add_co_u32_e32 v30, vcc, 0xd028000, v112
	s_nop 1
	v_addc_co_u32_e32 v31, vcc, 0, v113, vcc
	global_load_dwordx4 v[26:29], v[30:31], off
	s_nop 0
	global_load_dwordx4 v[30:33], v[30:31], off offset:64
	s_and_saveexec_b64 s[22:23], s[8:9]
	s_cbranch_execz .LBB0_1246
	v_lshl_add_u64 v[34:35], s[16:17], 0, v[106:107]
	v_add_co_u32_e32 v34, vcc, 0xe028000, v34
	s_nop 1
	v_addc_co_u32_e32 v35, vcc, 0, v35, vcc
	global_load_dwordx4 v[34:37], v[34:35], off

.LBB0_1247:
	s_and_saveexec_b64 s[22:23], s[8:9]
	s_cbranch_execz .LBB0_1249
	s_cmp_lg_u32 s29, -8
	s_cbranch_scc1 .Lc4_s_9
	s_waitcnt vmcnt(21)
.Lc4_s_9:
	s_waitcnt vmcnt(24)
	ds_write_b128 v131, v[58:61] offset:18432

.LBB0_1243:
	s_or_b64 exec, exec, s[98:99]
	v_mov_b32_e32 v122, s28
	ds_read_b128 v[136:139], v133 offset:13824
	ds_read_b64 v[122:123], v122 offset:24
	ds_read_b128 v[140:143], v133 offset:13888
	ds_read_b128 v[144:147], v133 offset:16128
	s_cmp_lg_u32 s29, -8
	s_cbranch_scc1 .Lc4_s_10
	s_waitcnt vmcnt(19)

.Lc4_e_10:
	v_mfma_f32_16x16x32_bf16 v[136:139], v[38:41], v[136:139], 0
	s_waitcnt lgkmcnt(2)
	v_add_f32_e32 v122, v134, v122
	v_max_f32_e32 v123, v123, v123
	v_max_f32_e32 v128, v122, v123
	v_sub_f32_e32 v122, v122, v128
	v_mul_f32_e32 v122, 0x3fb8aa3b, v122
	v_exp_f32_e32 v148, v122
	v_mul_f32_e32 v122, 0xbfb8aa3b, v128
	s_cmp_lg_u32 s29, -8
	s_cbranch_scc1 .Lc4_s_11
	s_waitcnt vmcnt(18)

.Lc4_e_11:
	v_mfma_f32_16x16x32_bf16 v[134:137], v[42:45], v[140:143], v[136:139]
	v_mul_f32_e64 v126, v126, v148
	v_mul_f32_e64 v127, v127, v148
	s_nop 0
	ds_read_b128 v[138:141], v133 offset:16192
	s_waitcnt lgkmcnt(1)
	v_mfma_f32_16x16x32_bf16 v[142:145], v[38:41], v[144:147], 0
	v_exp_f32_e32 v146, v122
	v_pk_mul_f32 v[122:123], v[124:125], v[148:149] op_sel_hi:[1,0]
	v_pk_fma_f32 v[124:125], v[134:135], v[146:147], v[126:127] op_sel_hi:[1,0,1]
	v_pk_fma_f32 v[122:123], v[136:137], v[146:147], v[122:123] op_sel_hi:[1,0,1]
	v_mfma_f32_16x16x32_bf16 v[134:137], v[38:41], v[86:89], 0
	s_waitcnt lgkmcnt(0)
	v_mfma_f32_16x16x32_bf16 v[138:141], v[42:45], v[138:141], v[142:145]
	v_mfma_f32_16x16x32_bf16 v[134:137], v[42:45], v[86:89], v[134:137]
	s_nop 6
	v_mul_f32_e64 v126, v146, v140
	v_mul_f32_e64 v127, v146, v141
	v_pk_mul_f32 v[138:139], v[146:147], v[138:139] op_sel_hi:[0,1]
	v_pk_fma_f32 v[116:117], v[116:117], v[148:149], v[126:127] op_sel_hi:[1,0,1]
	v_pk_fma_f32 v[120:121], v[120:121], v[148:149], v[138:139] op_sel_hi:[1,0,1]
	v_pk_mul_f32 v[126:127], v[146:147], v[136:137] op_sel_hi:[0,1]
	v_pk_mul_f32 v[134:135], v[146:147], v[134:135] op_sel_hi:[0,1]
	v_pk_fma_f32 v[114:115], v[114:115], v[148:149], v[126:127] op_sel_hi:[1,0,1]
	v_pk_fma_f32 v[118:119], v[118:119], v[148:149], v[134:135] op_sel_hi:[1,0,1]
	v_cvt_pk_bf16_f32 v134, v124, v125
	v_cvt_pk_bf16_f32 v136, v120, v121
	v_cvt_pk_bf16_f32 v135, v122, v123
	v_cvt_pk_bf16_f32 v137, v116, v117
	v_add_co_u32_e32 v126, vcc, 0x9020000, v110
	v_permlane16_swap_b32_e32 v134, v136
	v_permlane16_swap_b32_e32 v135, v137
	v_addc_co_u32_e32 v127, vcc, 0, v111, vcc
	ds_write_b128 v247, v[134:137] offset:8704
	s_waitcnt lgkmcnt(0)
	s_barrier
	s_add_i32 s22, s29, 12
	s_cmp_gt_u32 s22, 56
	s_cbranch_scc1 .LBB0_1257
	v_add_co_u32_e32 v42, vcc, 0xd02c000, v112
	s_nop 1
	v_addc_co_u32_e32 v43, vcc, 0, v113, vcc
	global_load_dwordx4 v[38:41], v[42:43], off
	s_nop 0
	global_load_dwordx4 v[42:45], v[42:43], off offset:64
	s_and_saveexec_b64 s[22:23], s[8:9]
	s_cbranch_execz .LBB0_1256
	v_lshl_add_u64 v[46:47], s[16:17], 0, v[106:107]
	v_add_co_u32_e32 v46, vcc, 0xe02c000, v46
	s_nop 1
	v_addc_co_u32_e32 v47, vcc, 0, v47, vcc
	global_load_dwordx4 v[46:49], v[46:47], off

.LBB0_1257:
	s_and_saveexec_b64 s[22:23], s[8:9]
	s_cbranch_execz .LBB0_1259
	s_cmp_lg_u32 s29, -8
	s_cbranch_scc1 .Lc4_s_12
	s_waitcnt vmcnt(22)
.Lc4_s_12:
	s_waitcnt vmcnt(24)
	ds_write_b128 v131, v[70:73] offset:23040

.LBB0_1253:
	s_or_b64 exec, exec, s[98:99]
	v_mov_b32_e32 v126, s28
	ds_read_b128 v[134:137], v133 offset:18432
	ds_read_b64 v[126:127], v126 offset:32
	ds_read_b128 v[138:141], v133 offset:18496
	ds_read_b128 v[142:145], v133 offset:20736
	s_cmp_lg_u32 s29, -8
	s_cbranch_scc1 .Lc4_s_13
	s_waitcnt vmcnt(20)

.Lc4_e_13:
	v_mfma_f32_16x16x32_bf16 v[134:137], v[50:53], v[134:137], 0
	s_waitcnt lgkmcnt(2)
	v_add_f32_e32 v128, v128, v126
	v_max_f32_e32 v126, v127, v127
	v_max_f32_e32 v126, v128, v126
	v_sub_f32_e32 v127, v128, v126
	v_mul_f32_e32 v127, 0x3fb8aa3b, v127
	v_exp_f32_e32 v128, v127
	v_mul_f32_e32 v127, 0xbfb8aa3b, v126
	s_cmp_lg_u32 s29, -8
	s_cbranch_scc1 .Lc4_s_14
	s_waitcnt vmcnt(19)

.Lc4_e_14:
	v_mfma_f32_16x16x32_bf16 v[134:137], v[54:57], v[138:141], v[134:137]
	v_exp_f32_e32 v146, v127
	ds_read_b128 v[138:141], v133 offset:20800
	v_pk_mul_f32 v[124:125], v[124:125], v[128:129] op_sel_hi:[1,0]
	s_waitcnt lgkmcnt(1)
	v_mfma_f32_16x16x32_bf16 v[142:145], v[50:53], v[142:145], 0
	v_mul_f32_e64 v122, v122, v128
	v_mul_f32_e64 v123, v123, v128
	s_nop 0
	v_pk_fma_f32 v[124:125], v[134:135], v[146:147], v[124:125] op_sel_hi:[1,0,1]
	v_pk_fma_f32 v[122:123], v[136:137], v[146:147], v[122:123] op_sel_hi:[1,0,1]
	v_mfma_f32_16x16x32_bf16 v[134:137], v[50:53], v[86:89], 0
	s_waitcnt lgkmcnt(0)
	v_mfma_f32_16x16x32_bf16 v[138:141], v[54:57], v[138:141], v[142:145]
	v_mfma_f32_16x16x32_bf16 v[134:137], v[54:57], v[86:89], v[134:137]
	s_nop 6
	v_mul_f32_e64 v140, v146, v140
	v_mul_f32_e64 v141, v146, v141
	v_pk_mul_f32 v[138:139], v[146:147], v[138:139] op_sel_hi:[0,1]
	v_pk_fma_f32 v[116:117], v[116:117], v[128:129], v[140:141] op_sel_hi:[1,0,1]
	v_pk_fma_f32 v[120:121], v[120:121], v[128:129], v[138:139] op_sel_hi:[1,0,1]
	v_pk_mul_f32 v[136:137], v[146:147], v[136:137] op_sel_hi:[0,1]
	v_pk_mul_f32 v[134:135], v[146:147], v[134:135] op_sel_hi:[0,1]
	v_pk_fma_f32 v[114:115], v[114:115], v[128:129], v[136:137] op_sel_hi:[1,0,1]
	v_pk_fma_f32 v[118:119], v[118:119], v[128:129], v[134:135] op_sel_hi:[1,0,1]
	v_cvt_pk_bf16_f32 v134, v124, v125
	v_cvt_pk_bf16_f32 v136, v120, v121
	v_cvt_pk_bf16_f32 v135, v122, v123
	v_cvt_pk_bf16_f32 v137, v116, v117
	v_add_co_u32_e32 v128, vcc, 0x9028000, v110
	v_permlane16_swap_b32_e32 v134, v136
	v_permlane16_swap_b32_e32 v135, v137
	v_addc_co_u32_e32 v129, vcc, 0, v111, vcc
	ds_write_b128 v247, v[134:137] offset:0
	s_waitcnt lgkmcnt(0)
	s_barrier
	s_add_i32 s22, s29, 13
	s_cmp_gt_u32 s22, 56
	s_cbranch_scc1 .LBB0_1267
	v_add_co_u32_e32 v54, vcc, 0xd030000, v112
	s_nop 1
	v_addc_co_u32_e32 v55, vcc, 0, v113, vcc
	global_load_dwordx4 v[50:53], v[54:55], off
	s_nop 0
	global_load_dwordx4 v[54:57], v[54:55], off offset:64
	s_and_saveexec_b64 s[22:23], s[8:9]
	s_cbranch_execz .LBB0_1266
	v_lshl_add_u64 v[58:59], s[16:17], 0, v[106:107]
	v_add_co_u32_e32 v58, vcc, 0xe030000, v58
	s_nop 1
	v_addc_co_u32_e32 v59, vcc, 0, v59, vcc
	global_load_dwordx4 v[58:61], v[58:59], off

.LBB0_1267:
	s_and_saveexec_b64 s[22:23], s[8:9]
	s_cbranch_execz .LBB0_1269
	s_cmp_lg_u32 s29, -8
	s_cbranch_scc1 .Lc4_s_15
	s_waitcnt vmcnt(23)
.Lc4_s_15:
	s_waitcnt vmcnt(24)
	ds_write_b128 v131, v[82:85] offset:27648

.LBB0_1263:
	s_or_b64 exec, exec, s[98:99]
	v_mov_b32_e32 v127, s28
	ds_read_b128 v[134:137], v133 offset:23040
	ds_read_b64 v[128:129], v127 offset:40
	ds_read_b128 v[138:141], v133 offset:23104
	ds_read_b128 v[142:145], v133 offset:25344
	s_cmp_lg_u32 s29, -8
	s_cbranch_scc1 .Lc4_s_16
	s_waitcnt vmcnt(21)

.Lc4_e_16:
	v_mfma_f32_16x16x32_bf16 v[134:137], v[62:65], v[134:137], 0
	s_waitcnt lgkmcnt(2)
	v_add_f32_e32 v126, v126, v128
	v_max_f32_e32 v127, v129, v129
	v_max_f32_e32 v128, v126, v127
	v_sub_f32_e32 v126, v126, v128
	v_mul_f32_e32 v126, 0x3fb8aa3b, v126
	v_exp_f32_e32 v146, v126
	v_mul_f32_e32 v126, 0xbfb8aa3b, v128
	s_cmp_lg_u32 s29, -8
	s_cbranch_scc1 .Lc4_s_17
	s_waitcnt vmcnt(20)

.Lc4_e_17:
	v_mfma_f32_16x16x32_bf16 v[134:137], v[66:69], v[138:141], v[134:137]
	v_exp_f32_e32 v148, v126
	ds_read_b128 v[138:141], v133 offset:25408
	v_pk_mul_f32 v[124:125], v[124:125], v[146:147] op_sel_hi:[1,0]
	s_waitcnt lgkmcnt(1)
	v_mfma_f32_16x16x32_bf16 v[142:145], v[62:65], v[142:145], 0
	v_mul_f32_e64 v122, v122, v146
	v_mul_f32_e64 v123, v123, v146
	s_nop 0
	v_pk_fma_f32 v[126:127], v[134:135], v[148:149], v[124:125] op_sel_hi:[1,0,1]
	v_pk_fma_f32 v[122:123], v[136:137], v[148:149], v[122:123] op_sel_hi:[1,0,1]
	v_mfma_f32_16x16x32_bf16 v[134:137], v[62:65], v[86:89], 0
	s_waitcnt lgkmcnt(0)
	v_mfma_f32_16x16x32_bf16 v[138:141], v[66:69], v[138:141], v[142:145]
	v_mfma_f32_16x16x32_bf16 v[134:137], v[66:69], v[86:89], v[134:137]
	s_nop 6
	v_mul_f32_e64 v124, v148, v140
	v_mul_f32_e64 v125, v148, v141
	v_pk_mul_f32 v[138:139], v[148:149], v[138:139] op_sel_hi:[0,1]
	v_pk_fma_f32 v[116:117], v[116:117], v[146:147], v[124:125] op_sel_hi:[1,0,1]
	v_pk_fma_f32 v[124:125], v[120:121], v[146:147], v[138:139] op_sel_hi:[1,0,1]
	v_pk_mul_f32 v[120:121], v[148:149], v[136:137] op_sel_hi:[0,1]
	v_pk_mul_f32 v[134:135], v[148:149], v[134:135] op_sel_hi:[0,1]
	v_pk_fma_f32 v[114:115], v[114:115], v[146:147], v[120:121] op_sel_hi:[1,0,1]
	v_pk_fma_f32 v[120:121], v[118:119], v[146:147], v[134:135] op_sel_hi:[1,0,1]
	v_cvt_pk_bf16_f32 v134, v126, v127
	v_cvt_pk_bf16_f32 v136, v124, v125
	v_cvt_pk_bf16_f32 v135, v122, v123
	v_cvt_pk_bf16_f32 v137, v116, v117
	v_add_co_u32_e32 v118, vcc, 0x9030000, v110
	v_permlane16_swap_b32_e32 v134, v136
	v_permlane16_swap_b32_e32 v135, v137
	v_addc_co_u32_e32 v119, vcc, 0, v111, vcc
	ds_write_b128 v247, v[134:137] offset:8704
	s_waitcnt lgkmcnt(0)
	s_barrier
	s_add_i32 s22, s29, 14
	s_cmp_gt_u32 s22, 56
	s_cbranch_scc1 .LBB0_1277
	v_add_co_u32_e32 v66, vcc, 0xd034000, v112
	s_nop 1
	v_addc_co_u32_e32 v67, vcc, 0, v113, vcc
	global_load_dwordx4 v[62:65], v[66:67], off
	s_nop 0
	global_load_dwordx4 v[66:69], v[66:67], off offset:64
	s_and_saveexec_b64 s[22:23], s[8:9]
	s_cbranch_execz .LBB0_1276
	v_lshl_add_u64 v[70:71], s[16:17], 0, v[106:107]
	v_add_co_u32_e32 v70, vcc, 0xe034000, v70
	s_nop 1
	v_addc_co_u32_e32 v71, vcc, 0, v71, vcc
	global_load_dwordx4 v[70:73], v[70:71], off

.Lch_rlx_18:
	s_cmp_lg_u32 s29, -8
	s_cbranch_scc1 .Lc4_s_18
	s_waitcnt vmcnt(23)

.LBB0_1273:
	s_or_b64 exec, exec, s[98:99]
	v_mov_b32_e32 v118, s28
	ds_read_b128 v[134:137], v133 offset:27648
	ds_read_b64 v[118:119], v118 offset:48
	ds_read_b128 v[138:141], v133 offset:27712
	ds_read_b128 v[146:149], v133 offset:29952
	s_cmp_lg_u32 s29, -8
	s_cbranch_scc1 .Lc4_s_19
	s_waitcnt vmcnt(22)

.Lc4_e_19:
	v_mfma_f32_16x16x32_bf16 v[142:145], v[74:77], v[134:137], 0
	s_waitcnt lgkmcnt(2)
	v_add_f32_e32 v118, v128, v118
	v_max_f32_e32 v119, v119, v119
	v_max_f32_e32 v134, v118, v119
	v_sub_f32_e32 v118, v118, v134
	v_mul_f32_e32 v118, 0x3fb8aa3b, v118
	v_exp_f32_e32 v150, v118
	v_mul_f32_e32 v118, 0xbfb8aa3b, v134
	s_cmp_lg_u32 s29, -8
	s_cbranch_scc1 .Lc4_s_20
	s_waitcnt vmcnt(21)

.Lc4_e_20:
	v_mfma_f32_16x16x32_bf16 v[136:139], v[78:81], v[138:141], v[142:145]
	v_mul_f32_e64 v122, v122, v150
	v_mul_f32_e64 v123, v123, v150
	s_nop 0
	ds_read_b128 v[140:143], v133 offset:30016
	s_waitcnt lgkmcnt(1)
	v_mfma_f32_16x16x32_bf16 v[144:147], v[74:77], v[146:149], 0
	v_exp_f32_e32 v148, v118
	v_pk_mul_f32 v[118:119], v[126:127], v[150:151] op_sel_hi:[1,0]
	v_pk_fma_f32 v[122:123], v[138:139], v[148:149], v[122:123] op_sel_hi:[1,0,1]
	v_pk_fma_f32 v[126:127], v[136:137], v[148:149], v[118:119] op_sel_hi:[1,0,1]
	v_mfma_f32_16x16x32_bf16 v[136:139], v[74:77], v[86:89], 0
	s_waitcnt lgkmcnt(0)
	v_mfma_f32_16x16x32_bf16 v[140:143], v[78:81], v[140:143], v[144:147]
	v_mfma_f32_16x16x32_bf16 v[136:139], v[78:81], v[86:89], v[136:139]
	s_nop 6
	v_mul_f32_e64 v118, v148, v142
	v_mul_f32_e64 v119, v148, v143
	v_pk_mul_f32 v[128:129], v[148:149], v[140:141] op_sel_hi:[0,1]
	v_pk_fma_f32 v[118:119], v[116:117], v[150:151], v[118:119] op_sel_hi:[1,0,1]
	v_pk_fma_f32 v[128:129], v[124:125], v[150:151], v[128:129] op_sel_hi:[1,0,1]
	v_pk_mul_f32 v[116:117], v[148:149], v[138:139] op_sel_hi:[0,1]
	v_pk_mul_f32 v[124:125], v[148:149], v[136:137] op_sel_hi:[0,1]
	v_pk_fma_f32 v[116:117], v[114:115], v[150:151], v[116:117] op_sel_hi:[1,0,1]
	v_cvt_pk_bf16_f32 v136, v126, v127
	v_cvt_pk_bf16_f32 v138, v128, v129
	v_cvt_pk_bf16_f32 v137, v122, v123
	v_cvt_pk_bf16_f32 v139, v118, v119
	v_add_co_u32_e32 v114, vcc, 0x9038000, v110
	v_pk_fma_f32 v[120:121], v[120:121], v[150:151], v[124:125] op_sel_hi:[1,0,1]
	v_permlane16_swap_b32_e32 v136, v138
	v_permlane16_swap_b32_e32 v137, v139
	v_addc_co_u32_e32 v115, vcc, 0, v111, vcc
	ds_write_b128 v247, v[136:139] offset:0
	s_waitcnt lgkmcnt(0)
	s_barrier
	s_add_i32 s24, s29, 15
	s_cmp_gt_u32 s24, 56
	s_cbranch_scc1 .LBB0_1287
	v_add_co_u32_e32 v78, vcc, 0xd038000, v112
	s_nop 1
	v_addc_co_u32_e32 v79, vcc, 0, v113, vcc
	global_load_dwordx4 v[74:77], v[78:79], off
	s_nop 0
	global_load_dwordx4 v[78:81], v[78:79], off offset:64
	s_and_saveexec_b64 s[22:23], s[8:9]
	s_cbranch_execz .LBB0_1286
	v_lshl_add_u64 v[82:83], s[16:17], 0, v[106:107]
	v_add_co_u32_e32 v82, vcc, 0xe038000, v82
	s_nop 1
	v_addc_co_u32_e32 v83, vcc, 0, v83, vcc
	global_load_dwordx4 v[82:85], v[82:83], off

.Lch_rlx_21:
	s_cmp_lg_u32 s29, -8
	s_cbranch_scc1 .Lc4_s_21
	s_waitcnt vmcnt(24)

.Lch_rlx_22:
	s_cmp_lg_u32 s29, -8
	s_cbranch_scc1 .Lc4_s_22
	s_waitcnt vmcnt(22)
.Lc4_s_22:
	s_cmp_lg_u64 s[8:9], 0
	s_cbranch_scc1 .Lc4_l_22
	s_waitcnt vmcnt(22) lgkmcnt(3)
	s_branch .Lc4_e_22
.Lc4_l_22:
	s_waitcnt vmcnt(30) lgkmcnt(3)
.Lc4_e_22:
	v_mfma_f32_16x16x32_bf16 v[140:143], v[98:101], v[112:115], 0
	s_waitcnt lgkmcnt(2)
	v_add_f32_e32 v112, v134, v124
	v_max_f32_e32 v113, v125, v125
	v_max_f32_e32 v115, v112, v113
	s_cmp_lg_u32 s29, 48
	s_cbranch_scc1 .Lch_rlx_23
	s_waitcnt vmcnt(7) lgkmcnt(1)
.Lch_rlx_23:
	s_cmp_lg_u32 s29, -8
	s_cbranch_scc1 .Lc4_s_23
	s_waitcnt vmcnt(21)
.Lc4_s_23:
	s_cmp_lg_u64 s[8:9], 0
	s_cbranch_scc1 .Lc4_l_23
	s_waitcnt vmcnt(21) lgkmcnt(1)
	s_branch .Lc4_e_23
.Lc4_l_23:
	s_waitcnt vmcnt(29) lgkmcnt(1)
.Lc4_e_23:
	v_mfma_f32_16x16x32_bf16 v[134:137], v[94:97], v[136:139], v[140:143]
	v_sub_f32_e32 v112, v112, v115
	v_mul_f32_e32 v112, 0x3fb8aa3b, v112
	v_exp_f32_e32 v112, v112
	ds_read_b128 v[138:141], v133 offset:34624
	s_waitcnt lgkmcnt(1)
	v_mfma_f32_16x16x32_bf16 v[142:145], v[98:101], v[144:147], 0
	v_mul_f32_e32 v113, 0xbfb8aa3b, v115
	v_exp_f32_e32 v114, v113
	v_pk_mul_f32 v[126:127], v[126:127], v[112:113] op_sel_hi:[1,0]
	v_mfma_f32_16x16x32_bf16 v[98:101], v[98:101], v[86:89], 0
	v_mul_f32_e64 v122, v122, v112
	v_mul_f32_e64 v123, v123, v112
	v_pk_fma_f32 v[126:127], v[134:135], v[114:115], v[126:127] op_sel_hi:[1,0,1]
	v_pk_fma_f32 v[124:125], v[136:137], v[114:115], v[122:123] op_sel_hi:[1,0,1]
	s_waitcnt lgkmcnt(0)
	v_mfma_f32_16x16x32_bf16 v[138:141], v[94:97], v[138:141], v[142:145]
	v_mfma_f32_16x16x32_bf16 v[94:97], v[94:97], v[86:89], v[98:101]
	s_nop 6
	v_mul_f32_e64 v122, v114, v140
	v_mul_f32_e64 v123, v114, v141
	v_pk_mul_f32 v[134:135], v[114:115], v[138:139] op_sel_hi:[0,1]
	v_pk_mul_f32 v[96:97], v[114:115], v[96:97] op_sel_hi:[0,1]
	v_pk_mul_f32 v[94:95], v[114:115], v[94:95] op_sel_hi:[0,1]
	v_pk_fma_f32 v[122:123], v[118:119], v[112:113], v[122:123] op_sel_hi:[1,0,1]
	v_pk_fma_f32 v[118:119], v[128:129], v[112:113], v[134:135] op_sel_hi:[1,0,1]
	v_pk_fma_f32 v[116:117], v[116:117], v[112:113], v[96:97] op_sel_hi:[1,0,1]
	v_pk_fma_f32 v[120:121], v[120:121], v[112:113], v[94:95] op_sel_hi:[1,0,1]
	s_cbranch_vccnz .LBB0_1214
	v_cvt_pk_bf16_f32 v94, v126, v127
	v_cvt_pk_bf16_f32 v96, v118, v119
	v_cvt_pk_bf16_f32 v95, v124, v125
	v_cvt_pk_bf16_f32 v97, v122, v123
	v_add_co_u32_e32 v98, vcc, 0x9040000, v110
	v_permlane16_swap_b32_e32 v94, v96
	v_permlane16_swap_b32_e32 v95, v97
	v_addc_co_u32_e32 v99, vcc, 0, v111, vcc
	global_store_dwordx4 v[98:99], v[94:97], off offset:2048
	s_and_saveexec_b64 s[22:23], s[10:11]
	s_cbranch_execz .LBB0_1292
	v_lshl_add_u64 v[96:97], s[16:17], 0, v[102:103]
	v_add_co_u32_e32 v96, vcc, 0x9048000, v96
	v_cvt_pk_bf16_f32 v94, v120, v121
	v_cvt_pk_bf16_f32 v95, v116, v117
	v_addc_co_u32_e32 v97, vcc, 0, v97, vcc
	global_store_dwordx2 v[96:97], v[94:95], off offset:2048
